# P0b transposes loop: prefetch loads stay in flight for the whole iteration; counted vmcnt(4) (the 4 stores issued after them) before the register rotation
# baseline (speedup 1.0000x reference)
; __device__ __forceinline__ unsigned pack2(float a, float b) { return (unsigned)f2bf(a) | ((unsigned)f2bf(b) << 16); }
; __device__ __forceinline__ void tr_store(const Params& p, char* ws, int job, int tid, const float* tile) {
;   TrJob t = tr_decode(p, ws, job);
;   const int kc = tid & 7, nn = tid >> 3;
; #pragma unroll
;   for (int pp = 0; pp < 2; ++pp) {
;     int n = nn + 32 * pp;
;     float v[8];
; #pragma unroll
;     for (int j = 0; j < 8; ++j) v[j] = tile[(kc * 8 + j) * 65 + n];
;     uint4 o;
;     o.x = pack2(v[0], v[1]); o.y = pack2(v[2], v[3]); o.z = pack2(v[4], v[5]); o.w = pack2(v[6], v[7]);
;     int gn = t.nt * 64 + n;
;     int drow = t.mode == 0 ? gn : gu_row(t.mode - 1, gn);
;     *(uint4*)&t.dst[(size_t)drow * t.K + t.kt * 64 + kc * 8] = o;
;   }
; }
; __device__ __forceinline__ void p0_transposes(const Params& p, char* smem, int bid, int nb, int jlo, int jhi) {
;     ...
;     tr_store(p, ws, j, tid, tileA);
;     tr_store(p, ws, j + 1, tid, tileB);
;     __syncthreads();
; #pragma unroll
;     for (int q = 0; q < 4; ++q) { c0[q] = n0[q]; c1[q] = n1[q]; }
;   }
.LBB0_173:
	s_lshl_b32 s33, s33, 6
	s_lshl_b32 s10, s11, 6
	v_add_u32_e32 v16, 0x4000, v78
	v_add_u32_e32 v24, s33, v76
	s_ashr_i32 s11, s10, 31
	v_or_b32_e32 v26, s55, v77
	ds_read2_b32 v[16:17], v16 offset0:129 offset1:194
	v_add_u32_e32 v22, 0x4400, v78
	v_lshlrev_b32_e32 v25, 1, v24
	s_lshl_b64 s[10:11], s[10:11], 1
	ds_read2_b32 v[18:19], v22 offset0:3 offset1:68
	ds_read2_b32 v[22:23], v22 offset0:133 offset1:198
	ds_read_b32 v27, v78 offset:16640
	ds_read_b32 v28, v78 offset:18460
	v_and_or_b32 v25, v25, s90, v26
	s_add_u32 s10, s58, s10
	v_cndmask_b32_e64 v24, v25, v24, s[52:53]
	s_addc_u32 s11, s59, s11
	v_mov_b32_e32 v69, v65
	v_ashrrev_i32_e32 v25, 31, v24
	v_lshl_add_u64 v[20:21], s[10:11], 0, v[68:69]
	v_mul_lo_u32 v29, s56, v25
	v_mul_lo_u32 v30, s57, v24
	v_mad_u64_u32 v[24:25], s[10:11], s56, v24, 0
	v_add3_u32 v25, v25, v29, v30
	s_waitcnt lgkmcnt(0)
	v_and_b32_sdwa v29, v17, v73 dst_sel:DWORD dst_unused:UNUSED_PAD src0_sel:WORD_1 src1_sel:DWORD
	v_and_b32_sdwa v30, v27, v73 dst_sel:DWORD dst_unused:UNUSED_PAD src0_sel:WORD_1 src1_sel:DWORD
	v_add3_u32 v27, v27, v30, s87
	v_add3_u32 v17, v17, v29, s87
	v_and_b32_sdwa v29, v18, v73 dst_sel:DWORD dst_unused:UNUSED_PAD src0_sel:WORD_1 src1_sel:DWORD
	v_and_b32_sdwa v30, v16, v73 dst_sel:DWORD dst_unused:UNUSED_PAD src0_sel:WORD_1 src1_sel:DWORD
	v_add3_u32 v18, v18, v29, s87
	v_add3_u32 v16, v16, v30, s87
	v_and_b32_e32 v18, 0xffff0000, v18
	v_and_b32_e32 v16, 0xffff0000, v16
	v_or_b32_sdwa v17, v18, v17 dst_sel:DWORD dst_unused:UNUSED_PAD src0_sel:DWORD src1_sel:WORD_1
	v_or_b32_sdwa v16, v16, v27 dst_sel:DWORD dst_unused:UNUSED_PAD src0_sel:DWORD src1_sel:WORD_1
	v_and_b32_sdwa v18, v23, v73 dst_sel:DWORD dst_unused:UNUSED_PAD src0_sel:WORD_1 src1_sel:DWORD
	v_and_b32_sdwa v27, v19, v73 dst_sel:DWORD dst_unused:UNUSED_PAD src0_sel:WORD_1 src1_sel:DWORD
	v_add3_u32 v27, v19, v27, s87
	v_add3_u32 v18, v23, v18, s87
	v_and_b32_sdwa v19, v28, v73 dst_sel:DWORD dst_unused:UNUSED_PAD src0_sel:WORD_1 src1_sel:DWORD
	v_and_b32_sdwa v23, v22, v73 dst_sel:DWORD dst_unused:UNUSED_PAD src0_sel:WORD_1 src1_sel:DWORD
	v_add3_u32 v19, v28, v19, s87
	v_add3_u32 v22, v22, v23, s87
	v_and_b32_e32 v19, 0xffff0000, v19
	v_and_b32_e32 v22, 0xffff0000, v22
	v_lshl_add_u64 v[24:25], v[24:25], 1, v[20:21]
	v_or_b32_sdwa v19, v19, v18 dst_sel:DWORD dst_unused:UNUSED_PAD src0_sel:DWORD src1_sel:WORD_1
	v_or_b32_sdwa v18, v22, v27 dst_sel:DWORD dst_unused:UNUSED_PAD src0_sel:DWORD src1_sel:WORD_1
	global_store_dwordx4 v[24:25], v[16:19], off
	v_add_u32_e32 v24, s33, v79
	v_lshlrev_b32_e32 v25, 1, v24
	v_add_u32_e32 v16, 0x4000, v80
	ds_read2_b32 v[16:17], v16 offset0:129 offset1:194
	v_and_or_b32 v25, v25, s90, v26
	v_cndmask_b32_e64 v24, v25, v24, s[52:53]
	v_ashrrev_i32_e32 v25, 31, v24
	v_add_u32_e32 v22, 0x4400, v80
	v_mul_lo_u32 v26, s56, v25
	v_mul_lo_u32 v29, s57, v24
	v_mad_u64_u32 v[24:25], s[10:11], s56, v24, 0
	ds_read2_b32 v[18:19], v22 offset0:3 offset1:68
	ds_read2_b32 v[22:23], v22 offset0:133 offset1:198
	ds_read_b32 v27, v78 offset:16768
	ds_read_b32 v28, v80 offset:18460
	v_add3_u32 v25, v25, v26, v29
	v_lshl_add_u64 v[20:21], v[24:25], 1, v[20:21]
	s_waitcnt lgkmcnt(0)
	v_and_b32_sdwa v24, v17, v73 dst_sel:DWORD dst_unused:UNUSED_PAD src0_sel:WORD_1 src1_sel:DWORD
	v_add3_u32 v17, v17, v24, s87
	v_and_b32_sdwa v24, v18, v73 dst_sel:DWORD dst_unused:UNUSED_PAD src0_sel:WORD_1 src1_sel:DWORD
	v_add3_u32 v18, v18, v24, s87
	v_and_b32_e32 v18, 0xffff0000, v18
	v_or_b32_sdwa v17, v18, v17 dst_sel:DWORD dst_unused:UNUSED_PAD src0_sel:DWORD src1_sel:WORD_1
	v_and_b32_sdwa v18, v23, v73 dst_sel:DWORD dst_unused:UNUSED_PAD src0_sel:WORD_1 src1_sel:DWORD
	v_and_b32_sdwa v24, v19, v73 dst_sel:DWORD dst_unused:UNUSED_PAD src0_sel:WORD_1 src1_sel:DWORD
	v_and_b32_sdwa v26, v16, v73 dst_sel:DWORD dst_unused:UNUSED_PAD src0_sel:WORD_1 src1_sel:DWORD
	v_add3_u32 v24, v19, v24, s87
	v_add3_u32 v18, v23, v18, s87
	v_and_b32_sdwa v19, v28, v73 dst_sel:DWORD dst_unused:UNUSED_PAD src0_sel:WORD_1 src1_sel:DWORD
	v_and_b32_sdwa v23, v22, v73 dst_sel:DWORD dst_unused:UNUSED_PAD src0_sel:WORD_1 src1_sel:DWORD
	v_and_b32_sdwa v25, v27, v73 dst_sel:DWORD dst_unused:UNUSED_PAD src0_sel:WORD_1 src1_sel:DWORD
	v_add3_u32 v16, v16, v26, s87
	v_add3_u32 v19, v28, v19, s87
	v_add3_u32 v22, v22, v23, s87
	v_add3_u32 v25, v27, v25, s87
	v_and_b32_e32 v16, 0xffff0000, v16
	v_and_b32_e32 v19, 0xffff0000, v19
	v_and_b32_e32 v22, 0xffff0000, v22
	v_or_b32_sdwa v16, v16, v25 dst_sel:DWORD dst_unused:UNUSED_PAD src0_sel:DWORD src1_sel:WORD_1
	v_or_b32_sdwa v19, v19, v18 dst_sel:DWORD dst_unused:UNUSED_PAD src0_sel:DWORD src1_sel:WORD_1
	v_or_b32_sdwa v18, v22, v24 dst_sel:DWORD dst_unused:UNUSED_PAD src0_sel:DWORD src1_sel:WORD_1
	global_store_dwordx4 v[20:21], v[16:19], off
	s_and_b64 vcc, exec, s[0:1]
	s_mov_b32 s97, s96
	s_waitcnt vmcnt(4)
	v_mov_b32_e32 v16, v0
	v_mov_b32_e32 v17, v1
	v_mov_b32_e32 v18, v2
	v_mov_b32_e32 v19, v3
	v_mov_b32_e32 v20, v4
	v_mov_b32_e32 v21, v5
	v_mov_b32_e32 v22, v6
	v_mov_b32_e32 v23, v7
	v_mov_b32_e32 v24, v8
	v_mov_b32_e32 v25, v9
	v_mov_b32_e32 v26, v10
	v_mov_b32_e32 v27, v11
	v_mov_b32_e32 v28, v12
	v_mov_b32_e32 v29, v13
	v_mov_b32_e32 v30, v14
	v_mov_b32_e32 v31, v15
	v_mov_b32_e32 v48, v32
	v_mov_b32_e32 v49, v33
	v_mov_b32_e32 v50, v34
	v_mov_b32_e32 v51, v35
	v_mov_b32_e32 v52, v36
	v_mov_b32_e32 v53, v37
	v_mov_b32_e32 v54, v38
	v_mov_b32_e32 v55, v39
	v_mov_b32_e32 v56, v40
	v_mov_b32_e32 v57, v41
	v_mov_b32_e32 v58, v42
	v_mov_b32_e32 v59, v43
	v_mov_b32_e32 v60, v44
	v_mov_b32_e32 v61, v45
	v_mov_b32_e32 v62, v46
	v_mov_b32_e32 v63, v47
	s_waitcnt lgkmcnt(0)
	s_barrier
	s_cbranch_vccnz .LBB0_139
